# attention loop: cross-half row-sum reduction deferred to unit end (per-half running l, fused fma update) + scalar rescale flag instead of per-tile v_cmp (on top of v039)
# speedup vs baseline: 1.0074x; 1.0052x over previous
; DEVFI void partialSM2(f32x16& p0, f32x16& p1, float& mhat, f32x16& negm, float& alpha, const float thr2, const bool first) {
;     float pmax = p0[0];
; #pragma unroll
;     for (int r = 1; r < 16; ++r) pmax = fmaxf(pmax, p0[r]);
; #pragma unroll
;     for (int r = 0; r < 16; ++r) pmax = fmaxf(pmax, p1[r]);
;     { auto rr = __builtin_amdgcn_permlane32_swap(__float_as_uint(pmax), __float_as_uint(pmax), false, false);
;       pmax = fmaxf(__uint_as_float(rr[0]), __uint_as_float(rr[1])); }
;     alpha = 1.f;
;     if (first || !__all(pmax <= thr2)) {
;         const float dl = first ? pmax : fmaxf(pmax, 0.f);
;         mhat += dl; alpha = first ? 1.f : __builtin_amdgcn_exp2f(-dl);
; #pragma unroll
;         for (int r = 0; r < 16; ++r) { p0[r] -= dl; p1[r] -= dl; }
; #pragma unroll
;         for (int r = 0; r < 16; ++r) negm[r] = -mhat;
;         asm volatile("" : "+v"(negm));
;     }
; DEVFI void finishSM(f32x16& p0, f32x16& p1, float alpha, float& l_reg, bf16x8& pa0, bf16x8& pa1, bf16x8& pa2, bf16x8& pa3) {
; #pragma unroll
;     for (int r = 0; r < 16; ++r) p1[r] = __builtin_amdgcn_exp2f(p1[r]);
;     float ps = 0;
; #pragma unroll
;     for (int r = 0; r < 16; ++r) ps += p0[r];
; #pragma unroll
;     for (int r = 0; r < 16; ++r) ps += p1[r];
;     { auto rr = __builtin_amdgcn_permlane32_swap(__float_as_uint(ps), __float_as_uint(ps), false, false);
;       ps = __uint_as_float(rr[0]) + __uint_as_float(rr[1]); }
;     l_reg = l_reg * alpha + ps;
;     ...
;     PK4(p0, 0, pa0); PK4(p0, 8, pa1); PK4(p1, 0, pa2); PK4(p1, 8, pa3);
.LBB0_1151:
	ds_read_b128 v[0:3], v177 offset:32768
	ds_read_b128 v[4:7], v177 offset:40960
	v_add_f32_e32 v8, v203, v205
	v_add_f32_e32 v8, v189, v8
	s_waitcnt lgkmcnt(1)
	v_mfma_f32_32x32x16_bf16 v[94:109], v[0:3], v[130:133], v[46:61]
	v_add_f32_e32 v8, v204, v8
	v_add_f32_e32 v8, v187, v8
	v_add_f32_e32 v8, v202, v8
	v_add_f32_e32 v8, v186, v8
	v_add_f32_e32 v8, v188, v8
	v_add_f32_e32 v8, v183, v8
	v_add_f32_e32 v8, v185, v8
	s_waitcnt lgkmcnt(0)
	v_mfma_f32_32x32x16_bf16 v[78:93], v[4:7], v[130:133], v[46:61]
	ds_read_b128 v[0:3], v178 offset:32768
	ds_read_b128 v[4:7], v178 offset:40960
	v_add_f32_e32 v8, v163, v8
	v_add_f32_e32 v8, v184, v8
	v_add_f32_e32 v8, v161, v8
	v_add_f32_e32 v8, v182, v8
	v_add_f32_e32 v8, v160, v8
	v_add_f32_e32 v8, v162, v8
	s_waitcnt lgkmcnt(1)
	v_mfma_f32_32x32x16_bf16 v[94:109], v[0:3], v[126:129], v[94:109]
	v_exp_f32_e32 v70, v70
	v_exp_f32_e32 v71, v71
	v_exp_f32_e32 v72, v72
	v_exp_f32_e32 v73, v73
	v_exp_f32_e32 v74, v74
	v_exp_f32_e32 v75, v75
	v_exp_f32_e32 v76, v76
	s_waitcnt lgkmcnt(0)
	v_mfma_f32_32x32x16_bf16 v[78:93], v[4:7], v[126:129], v[78:93]
	ds_read_b128 v[0:3], v176 offset:32768
	ds_read_b128 v[4:7], v176 offset:40960
	v_exp_f32_e32 v77, v77
	s_waitcnt lgkmcnt(1)
	v_mfma_f32_32x32x16_bf16 v[94:109], v[0:3], v[122:125], v[94:109]
	s_waitcnt lgkmcnt(0)
	v_mfma_f32_32x32x16_bf16 v[78:93], v[4:7], v[122:125], v[78:93]
	ds_read_b128 v[0:3], v175 offset:32768
	ds_read_b128 v[4:7], v175 offset:40960
	s_waitcnt lgkmcnt(1)
	v_mfma_f32_32x32x16_bf16 v[94:109], v[0:3], v[118:121], v[94:109]
	s_waitcnt lgkmcnt(0)
	v_mfma_f32_32x32x16_bf16 v[78:93], v[4:7], v[118:121], v[78:93]
	ds_read_b128 v[0:3], v174 offset:32768
	ds_read_b128 v[4:7], v174 offset:40960
	s_waitcnt lgkmcnt(1)
	v_mfma_f32_32x32x16_bf16 v[94:109], v[0:3], v[114:117], v[94:109]
	s_waitcnt lgkmcnt(0)
	v_mfma_f32_32x32x16_bf16 v[78:93], v[4:7], v[114:117], v[78:93]
	ds_read_b128 v[0:3], v172 offset:32768
	ds_read_b128 v[4:7], v172 offset:40960
	s_waitcnt lgkmcnt(1)
	v_mfma_f32_32x32x16_bf16 v[94:109], v[0:3], v[110:113], v[94:109]
	v_exp_f32_e32 v0, v62
	v_exp_f32_e32 v1, v63
	v_exp_f32_e32 v2, v64
	v_exp_f32_e32 v3, v65
	v_add_f32_e32 v8, v0, v8
	v_add_f32_e32 v8, v1, v8
	v_add_f32_e32 v8, v2, v8
	s_waitcnt lgkmcnt(0)
	v_mfma_f32_32x32x16_bf16 v[78:93], v[4:7], v[110:113], v[78:93]
	v_exp_f32_e32 v4, v66
	v_exp_f32_e32 v5, v67
	v_exp_f32_e32 v6, v68
	v_exp_f32_e32 v7, v69
	v_add_f32_e32 v8, v3, v8
	v_add_f32_e32 v8, v4, v8
	v_add_f32_e32 v8, v5, v8
	v_add_f32_e32 v8, v6, v8
	v_add_f32_e32 v8, v7, v8
	v_add_f32_e32 v8, v70, v8
	v_add_f32_e32 v8, v71, v8
	v_add_f32_e32 v8, v72, v8
	v_add_f32_e32 v8, v73, v8
	v_add_f32_e32 v8, v74, v8
	v_add_f32_e32 v8, v75, v8
	v_add_f32_e32 v8, v76, v8
	v_add_f32_e32 v13, v77, v8
	v_cvt_pk_bf16_f32 v8, v203, v205
	v_cvt_pk_bf16_f32 v9, v189, v204
	v_cvt_pk_bf16_f32 v10, v187, v202
	v_cvt_pk_bf16_f32 v11, v186, v188
	v_cvt_pk_bf16_f32 v62, v183, v185
	v_cvt_pk_bf16_f32 v63, v163, v184
	v_cvt_pk_bf16_f32 v64, v161, v182
	v_cvt_pk_bf16_f32 v65, v160, v162
	v_cvt_pk_bf16_f32 v66, v0, v1
	v_cvt_pk_bf16_f32 v67, v2, v3
	v_cvt_pk_bf16_f32 v68, v4, v5
	v_cvt_pk_bf16_f32 v69, v6, v7
	v_cvt_pk_bf16_f32 v70, v70, v71
	v_cvt_pk_bf16_f32 v71, v72, v73
	v_cvt_pk_bf16_f32 v72, v74, v75
	v_cvt_pk_bf16_f32 v73, v76, v77
	s_nop 1
	v_permlane32_swap_b32_e32 v8, v10
	v_permlane32_swap_b32_e32 v9, v11
	v_permlane32_swap_b32_e32 v62, v64
	v_permlane32_swap_b32_e32 v63, v65
	v_permlane32_swap_b32_e32 v66, v68
	v_permlane32_swap_b32_e32 v67, v69
	v_permlane32_swap_b32_e32 v70, v72
	v_permlane32_swap_b32_e32 v71, v73
	s_add_u32 s100, s10, 0x2cc48000
	s_addc_u32 s101, s11, 0
	s_nop 0
	global_load_dwordx4 v[0:3], v158, s[100:101]
	s_and_saveexec_b64 s[0:1], s[42:43]
	s_cbranch_execz .LBB0_1153
	global_load_dwordx4 v[138:141], v154, s[100:101]
.LBB0_1153:
	s_or_b64 exec, exec, s[0:1]
	s_add_u32 s100, s10, 0x2fc30000
	s_addc_u32 s101, s11, 0
	s_nop 0
	global_load_dwordx4 v[4:7], v156, s[100:101]
	ds_read_b64_tr_b16 v[74:75], v171 offset:0
	ds_read_b64_tr_b16 v[76:77], v171 offset:0x400
	ds_read_b64_tr_b16 v[182:183], v171 offset:0x800
	ds_read_b64_tr_b16 v[184:185], v171 offset:0xc00
	ds_read_b64_tr_b16 v[186:187], v171 offset:0x1000
	ds_read_b64_tr_b16 v[188:189], v171 offset:0x1400
	ds_read_b64_tr_b16 v[202:203], v171 offset:0x1800
	ds_read_b64_tr_b16 v[204:205], v171 offset:0x1c00
	s_waitcnt lgkmcnt(6)
	s_nop 0
	v_mfma_f32_32x32x16_bf16 v[30:45], v[8:11], v[74:77], v[30:45]
	ds_read_b64_tr_b16 v[74:75], v171 offset:0x200
	ds_read_b64_tr_b16 v[76:77], v171 offset:0x600
	s_waitcnt lgkmcnt(6)
	v_mfma_f32_32x32x16_bf16 v[30:45], v[62:65], v[182:185], v[30:45]
	ds_read_b64_tr_b16 v[182:183], v171 offset:0xa00
	ds_read_b64_tr_b16 v[184:185], v171 offset:0xe00
	s_waitcnt lgkmcnt(6)
	v_mfma_f32_32x32x16_bf16 v[30:45], v[66:69], v[186:189], v[30:45]
	ds_read_b64_tr_b16 v[186:187], v171 offset:0x1200
	ds_read_b64_tr_b16 v[188:189], v171 offset:0x1600
	s_waitcnt lgkmcnt(6)
	v_mfma_f32_32x32x16_bf16 v[30:45], v[70:73], v[202:205], v[30:45]
	ds_read_b64_tr_b16 v[202:203], v171 offset:0x1a00
	ds_read_b64_tr_b16 v[204:205], v171 offset:0x1e00
	s_waitcnt lgkmcnt(6)
	v_mfma_f32_32x32x16_bf16 v[14:29], v[8:11], v[74:77], v[14:29]
	v_max_f32_e32 v8, v94, v95
	v_max3_f32 v8, v8, v96, v97
	v_max3_f32 v8, v8, v98, v99
	v_max3_f32 v8, v8, v100, v101
	v_max3_f32 v8, v8, v102, v103
	s_waitcnt lgkmcnt(4)
	v_mfma_f32_32x32x16_bf16 v[14:29], v[62:65], v[182:185], v[14:29]
	v_max3_f32 v8, v8, v104, v105
	v_max3_f32 v8, v8, v106, v107
	v_max3_f32 v8, v8, v108, v109
	v_max3_f32 v8, v8, v78, v79
	v_max3_f32 v8, v8, v80, v81
	v_max3_f32 v8, v8, v82, v83
	v_max3_f32 v8, v8, v84, v85
	s_waitcnt lgkmcnt(2)
	v_mfma_f32_32x32x16_bf16 v[14:29], v[66:69], v[186:189], v[14:29]
	v_max3_f32 v8, v8, v86, v87
	v_max3_f32 v8, v8, v88, v89
	v_max3_f32 v8, v8, v90, v91
	v_max3_f32 v8, v8, v92, v93
	v_mov_b32_e32 v9, v8
	s_nop 1
	v_permlane32_swap_b32_e32 v8, v9
	s_waitcnt lgkmcnt(0)
	v_mfma_f32_32x32x16_bf16 v[14:29], v[70:73], v[202:205], v[14:29]
	v_max_f32_e32 v8, v8, v9
	v_cmp_ge_f32_e32 vcc, s33, v8
	s_cmp_eq_u64 vcc, exec
	s_cselect_b32 s100, 0, 1
	v_mov_b32_e32 v181, 1.0
	s_cbranch_scc1 .LBB0_1155
; DEVFI void partialSM2(f32x16& p0, f32x16& p1, float& mhat, f32x16& negm, float& alpha, const float thr2, const bool first) {
;     float pmax = p0[0];
; #pragma unroll
;     for (int r = 1; r < 16; ++r) pmax = fmaxf(pmax, p0[r]);
; #pragma unroll
;     for (int r = 0; r < 16; ++r) pmax = fmaxf(pmax, p1[r]);
;     { auto rr = __builtin_amdgcn_permlane32_swap(__float_as_uint(pmax), __float_as_uint(pmax), false, false);
;       pmax = fmaxf(__uint_as_float(rr[0]), __uint_as_float(rr[1])); }
;     alpha = 1.f;
;     if (first || !__all(pmax <= thr2)) {
;         const float dl = first ? pmax : fmaxf(pmax, 0.f);
;         mhat += dl; alpha = first ? 1.f : __builtin_amdgcn_exp2f(-dl);
; #pragma unroll
;         for (int r = 0; r < 16; ++r) { p0[r] -= dl; p1[r] -= dl; }
; #pragma unroll
;         for (int r = 0; r < 16; ++r) negm[r] = -mhat;
;         asm volatile("" : "+v"(negm));
;     }
	v_max_f32_e32 v8, v8, v8
	v_max_f32_e32 v8, 0, v8
	v_exp_f32_e64 v181, -v8
	v_add_f32_e32 v168, v168, v8
	v_xor_b32_e32 v46, 0x80000000, v168
	v_pk_add_f32 v[94:95], v[94:95], v[8:9] op_sel_hi:[1,0] neg_lo:[0,1] neg_hi:[0,1]
	v_pk_add_f32 v[96:97], v[96:97], v[8:9] op_sel_hi:[1,0] neg_lo:[0,1] neg_hi:[0,1]
	v_pk_add_f32 v[98:99], v[98:99], v[8:9] op_sel_hi:[1,0] neg_lo:[0,1] neg_hi:[0,1]
	v_pk_add_f32 v[100:101], v[100:101], v[8:9] op_sel_hi:[1,0] neg_lo:[0,1] neg_hi:[0,1]
	v_pk_add_f32 v[102:103], v[102:103], v[8:9] op_sel_hi:[1,0] neg_lo:[0,1] neg_hi:[0,1]
	v_pk_add_f32 v[104:105], v[104:105], v[8:9] op_sel_hi:[1,0] neg_lo:[0,1] neg_hi:[0,1]
	v_pk_add_f32 v[106:107], v[106:107], v[8:9] op_sel_hi:[1,0] neg_lo:[0,1] neg_hi:[0,1]
	v_pk_add_f32 v[108:109], v[108:109], v[8:9] op_sel_hi:[1,0] neg_lo:[0,1] neg_hi:[0,1]
	v_sub_f32_e32 v93, v93, v8
	v_sub_f32_e32 v92, v92, v8
	v_sub_f32_e32 v91, v91, v8
	v_sub_f32_e32 v90, v90, v8
	v_sub_f32_e32 v89, v89, v8
	v_sub_f32_e32 v88, v88, v8
	v_sub_f32_e32 v87, v87, v8
	v_sub_f32_e32 v86, v86, v8
	v_sub_f32_e32 v85, v85, v8
	v_sub_f32_e32 v84, v84, v8
	v_sub_f32_e32 v83, v83, v8
	v_sub_f32_e32 v82, v82, v8
	v_sub_f32_e32 v81, v81, v8
	v_sub_f32_e32 v80, v80, v8
	v_sub_f32_e32 v79, v79, v8
	v_sub_f32_e32 v78, v78, v8
	v_mov_b32_e32 v47, v46
	v_mov_b32_e32 v48, v46
	v_mov_b32_e32 v49, v46
	v_mov_b32_e32 v50, v46
	v_mov_b32_e32 v51, v46
	v_mov_b32_e32 v52, v46
	v_mov_b32_e32 v53, v46
	v_mov_b32_e32 v54, v46
	v_mov_b32_e32 v55, v46
	v_mov_b32_e32 v56, v46
	v_mov_b32_e32 v57, v46
	v_mov_b32_e32 v58, v46
	v_mov_b32_e32 v59, v46
	v_mov_b32_e32 v60, v46
	v_mov_b32_e32 v61, v46
.LBB0_1155:
	s_barrier
	s_waitcnt vmcnt(2)
	ds_write_b128 v169, v[146:149]
	ds_write_b128 v170, v[142:145] offset:16384
	s_and_saveexec_b64 s[0:1], s[42:43]
	ds_write_b128 v173, v[134:137] offset:16384
	s_or_b64 exec, exec, s[0:1]
	s_cmp_eq_u32 s100, 0
	s_cbranch_scc1 .LBB0_1161
	s_and_saveexec_b64 s[0:1], s[40:41]
	ds_write_b32 v165, v181 offset:49280
	s_or_b64 exec, exec, s[0:1]
	s_waitcnt lgkmcnt(0)
	v_add_u32_e32 v70, v153, v150
	ds_read_b128 v[8:11], v70 offset:49376
	ds_read_b128 v[62:65], v70 offset:49344
	ds_read_b128 v[66:69], v70 offset:49312
	ds_read_b128 v[70:73], v70 offset:49280
	s_waitcnt lgkmcnt(3)
	v_pk_mul_f32 v[42:43], v[42:43], v[8:9]
	s_waitcnt lgkmcnt(2)
	v_pk_mul_f32 v[38:39], v[38:39], v[62:63]
	s_waitcnt lgkmcnt(1)
	v_pk_mul_f32 v[34:35], v[34:35], v[66:67]
	v_pk_mul_f32 v[44:45], v[44:45], v[10:11]
	v_pk_mul_f32 v[40:41], v[40:41], v[64:65]
	v_pk_mul_f32 v[36:37], v[36:37], v[68:69]
	s_waitcnt lgkmcnt(0)
	v_pk_mul_f32 v[32:33], v[32:33], v[72:73]
	v_pk_mul_f32 v[30:31], v[30:31], v[70:71]
	v_pk_mul_f32 v[26:27], v[26:27], v[8:9]
	v_pk_mul_f32 v[22:23], v[22:23], v[62:63]
	v_pk_mul_f32 v[18:19], v[18:19], v[66:67]
	v_pk_mul_f32 v[28:29], v[28:29], v[10:11]
	v_pk_mul_f32 v[24:25], v[24:25], v[64:65]
	v_pk_mul_f32 v[20:21], v[20:21], v[68:69]
	v_pk_mul_f32 v[16:17], v[16:17], v[72:73]
	v_pk_mul_f32 v[14:15], v[14:15], v[70:71]
; DEVFI void finishSM(f32x16& p0, f32x16& p1, float alpha, float& l_reg, bf16x8& pa0, bf16x8& pa1, bf16x8& pa2, bf16x8& pa3) {
; #pragma unroll
;     for (int r = 0; r < 16; ++r) p1[r] = __builtin_amdgcn_exp2f(p1[r]);
;     float ps = 0;
; #pragma unroll
;     for (int r = 0; r < 16; ++r) ps += p0[r];
; #pragma unroll
;     for (int r = 0; r < 16; ++r) ps += p1[r];
;     { auto rr = __builtin_amdgcn_permlane32_swap(__float_as_uint(ps), __float_as_uint(ps), false, false);
;       ps = __uint_as_float(rr[0]) + __uint_as_float(rr[1]); }
;     l_reg = l_reg * alpha + ps;
;     ...
;     PK4(p0, 0, pa0); PK4(p0, 8, pa1); PK4(p1, 0, pa2); PK4(p1, 8, pa3);
.LBB0_1161:
	v_exp_f32_e32 v8, v94
	v_exp_f32_e32 v9, v96
	v_exp_f32_e32 v10, v98
	v_exp_f32_e32 v11, v100
	v_exp_f32_e32 v205, v95
	v_exp_f32_e32 v204, v97
	v_exp_f32_e32 v203, v99
	v_exp_f32_e32 v202, v101
	v_exp_f32_e32 v187, v102
	v_exp_f32_e32 v189, v103
	v_exp_f32_e32 v185, v104
	v_exp_f32_e32 v188, v105
	v_exp_f32_e32 v183, v106
	v_exp_f32_e32 v186, v107
	v_exp_f32_e32 v182, v108
	v_exp_f32_e32 v184, v109
	s_waitcnt lgkmcnt(0)
	s_barrier
	ds_read_b128 v[62:65], v177 offset:16384
	ds_read_b128 v[206:209], v177 offset:24576
	v_exp_f32_e32 v190, v78
	v_add_f32_e32 v78, v8, v205
	s_waitcnt lgkmcnt(1)
	v_mfma_f32_32x32x16_bf16 v[94:109], v[62:65], v[130:133], v[46:61]
	v_add_f32_e32 v78, v9, v78
	v_add_f32_e32 v78, v204, v78
	v_add_f32_e32 v78, v10, v78
	v_add_f32_e32 v78, v203, v78
	v_add_f32_e32 v78, v11, v78
	v_add_f32_e32 v78, v202, v78
	v_add_f32_e32 v78, v187, v78
	s_waitcnt lgkmcnt(0)
	v_mfma_f32_32x32x16_bf16 v[62:77], v[206:209], v[130:133], v[46:61]
	ds_read_b128 v[206:209], v178 offset:16384
	ds_read_b128 v[210:213], v178 offset:24576
	v_add_f32_e32 v78, v189, v78
	v_add_f32_e32 v78, v185, v78
	v_add_f32_e32 v78, v188, v78
	v_add_f32_e32 v78, v183, v78
	v_exp_f32_e32 v191, v79
	v_add_f32_e32 v78, v186, v78
	s_waitcnt lgkmcnt(1)
	v_mfma_f32_32x32x16_bf16 v[94:109], v[206:209], v[126:129], v[94:109]
	v_add_f32_e32 v78, v182, v78
	v_add_f32_e32 v78, v184, v78
	v_add_f32_e32 v78, v190, v78
	v_add_f32_e32 v78, v191, v78
	v_exp_f32_e32 v85, v85
	v_exp_f32_e32 v86, v86
	v_exp_f32_e32 v87, v87
	s_waitcnt lgkmcnt(0)
	v_mfma_f32_32x32x16_bf16 v[62:77], v[210:213], v[126:129], v[62:77]
	ds_read_b128 v[206:209], v176 offset:16384
	ds_read_b128 v[210:213], v176 offset:24576
	v_exp_f32_e32 v88, v88
	v_exp_f32_e32 v89, v89
	v_exp_f32_e32 v92, v92
	v_exp_f32_e32 v93, v93
	s_waitcnt lgkmcnt(1)
	v_mfma_f32_32x32x16_bf16 v[94:109], v[206:209], v[122:125], v[94:109]
	s_waitcnt lgkmcnt(0)
	v_mfma_f32_32x32x16_bf16 v[62:77], v[210:213], v[122:125], v[62:77]
	ds_read_b128 v[206:209], v175 offset:16384
	ds_read_b128 v[210:213], v175 offset:24576
	s_waitcnt lgkmcnt(1)
	v_mfma_f32_32x32x16_bf16 v[94:109], v[206:209], v[118:121], v[94:109]
	s_waitcnt lgkmcnt(0)
	v_mfma_f32_32x32x16_bf16 v[62:77], v[210:213], v[118:121], v[62:77]
	ds_read_b128 v[206:209], v174 offset:16384
	ds_read_b128 v[210:213], v174 offset:24576
	s_waitcnt lgkmcnt(1)
	v_mfma_f32_32x32x16_bf16 v[94:109], v[206:209], v[114:117], v[94:109]
	s_waitcnt lgkmcnt(0)
	v_mfma_f32_32x32x16_bf16 v[62:77], v[210:213], v[114:117], v[62:77]
	ds_read_b128 v[206:209], v172 offset:16384
	ds_read_b128 v[210:213], v172 offset:24576
	v_cvt_pk_bf16_f32 v8, v8, v205
	v_cvt_pk_bf16_f32 v9, v9, v204
	v_cvt_pk_bf16_f32 v10, v10, v203
	v_cvt_pk_bf16_f32 v11, v11, v202
	s_nop 0
	v_permlane32_swap_b32_e32 v8, v10
	s_waitcnt lgkmcnt(1)
	v_mfma_f32_32x32x16_bf16 v[94:109], v[206:209], v[110:113], v[94:109]
	v_exp_f32_e32 v206, v80
	v_exp_f32_e32 v207, v81
	v_exp_f32_e32 v208, v82
	v_exp_f32_e32 v209, v83
	v_add_f32_e32 v78, v206, v78
	v_add_f32_e32 v78, v207, v78
	v_add_f32_e32 v78, v208, v78
	s_waitcnt lgkmcnt(0)
	v_mfma_f32_32x32x16_bf16 v[62:77], v[210:213], v[110:113], v[62:77]
	v_exp_f32_e32 v210, v84
	v_add_f32_e32 v78, v209, v78
	v_exp_f32_e32 v211, v90
	v_exp_f32_e32 v212, v91
	v_add_f32_e32 v78, v210, v78
	v_add_f32_e32 v78, v85, v78
	v_add_f32_e32 v78, v86, v78
	v_add_f32_e32 v78, v87, v78
	v_add_f32_e32 v78, v88, v78
	v_add_f32_e32 v78, v89, v78
	v_add_f32_e32 v78, v211, v78
	v_add_f32_e32 v78, v212, v78
	v_add_f32_e32 v78, v92, v78
	v_add_f32_e32 v90, v93, v78
	v_cvt_pk_bf16_f32 v78, v187, v189
	v_cvt_pk_bf16_f32 v79, v185, v188
	v_cvt_pk_bf16_f32 v80, v183, v186
	v_cvt_pk_bf16_f32 v81, v182, v184
	v_cvt_pk_bf16_f32 v82, v190, v191
	v_cvt_pk_bf16_f32 v83, v206, v207
	v_cvt_pk_bf16_f32 v84, v208, v209
	v_cvt_pk_bf16_f32 v85, v210, v85
	v_cvt_pk_bf16_f32 v86, v86, v87
	v_cvt_pk_bf16_f32 v87, v88, v89
	v_cvt_pk_bf16_f32 v88, v211, v212
	v_cvt_pk_bf16_f32 v89, v92, v93
	s_nop 1
	v_permlane32_swap_b32_e32 v9, v11
	v_permlane32_swap_b32_e32 v78, v80
	v_permlane32_swap_b32_e32 v79, v81
	v_permlane32_swap_b32_e32 v82, v84
	v_permlane32_swap_b32_e32 v83, v85
	v_permlane32_swap_b32_e32 v86, v88
	v_permlane32_swap_b32_e32 v87, v89
	s_cmp_ge_u32 s18, s59
	s_cselect_b64 s[0:1], -1, 0
	s_and_b64 vcc, exec, s[0:1]
	s_cbranch_vccnz .LBB0_1165
	s_add_u32 s100, s10, 0x2cc60000
	s_addc_u32 s101, s11, 0
	s_nop 0
	global_load_dwordx4 v[142:145], v158, s[100:101]
	s_and_saveexec_b64 s[16:17], s[42:43]
	s_cbranch_execz .LBB0_1164
	global_load_dwordx4 v[134:137], v154, s[100:101]

; #define SBAR() __builtin_amdgcn_sched_barrier(0)
; template <int OFF> DEVFI s16x4 tr_read(int vb) { s16x4 r; asm volatile("ds_read_b64_tr_b16 %0, %1 offset:%2" : "=&v"(r) : "v"(vb), "i"(OFF) : "memory"); return r; }
; template <int NCB, int D0> DEVFI void pv_one(f32x16& od, int vb, bf16x8 pa0, bf16x8 pa1, bf16x8 pa2, bf16x8 pa3) {
;     ...
;     const s16x4 l0 = tr_read<VOFF(0, 0)>(vb), h0 = tr_read<VOFF(0, 1)>(vb), l1 = tr_read<VOFF(1, 0)>(vb), h1 = tr_read<VOFF(1, 1)>(vb);
;     const s16x4 l2 = tr_read<VOFF(2, 0)>(vb), h2 = tr_read<VOFF(2, 1)>(vb), l3 = tr_read<VOFF(3, 0)>(vb), h3 = tr_read<VOFF(3, 1)>(vb);
;     ...
;     asm volatile("s_waitcnt lgkmcnt(0)" ::: "memory"); SBAR();
;     ...
;     od = __builtin_amdgcn_mfma_f32_32x32x16_bf16(pa0, PK(l0, h0), od, 0, 0, 0);
;     od = __builtin_amdgcn_mfma_f32_32x32x16_bf16(pa1, PK(l1, h1), od, 0, 0, 0);
;     od = __builtin_amdgcn_mfma_f32_32x32x16_bf16(pa2, PK(l2, h2), od, 0, 0, 0);
;     od = __builtin_amdgcn_mfma_f32_32x32x16_bf16(pa3, PK(l3, h3), od, 0, 0, 0);
;     ...
; }
.LBB0_1165:
	ds_read_b64_tr_b16 v[160:161], v167 offset:0
	ds_read_b64_tr_b16 v[162:163], v167 offset:0x400
	ds_read_b64_tr_b16 v[182:183], v167 offset:0x800
	ds_read_b64_tr_b16 v[184:185], v167 offset:0xc00
	ds_read_b64_tr_b16 v[186:187], v167 offset:0x1000
	ds_read_b64_tr_b16 v[188:189], v167 offset:0x1400
	ds_read_b64_tr_b16 v[202:203], v167 offset:0x1800
	ds_read_b64_tr_b16 v[204:205], v167 offset:0x1c00
	s_waitcnt lgkmcnt(6)
	s_nop 0
	v_mfma_f32_32x32x16_bf16 v[30:45], v[8:11], v[160:163], v[30:45]
	ds_read_b64_tr_b16 v[160:161], v167 offset:0x200
	ds_read_b64_tr_b16 v[162:163], v167 offset:0x600
	s_waitcnt lgkmcnt(6)
	v_mfma_f32_32x32x16_bf16 v[30:45], v[78:81], v[182:185], v[30:45]
	ds_read_b64_tr_b16 v[182:183], v167 offset:0xa00
	ds_read_b64_tr_b16 v[184:185], v167 offset:0xe00
	s_waitcnt lgkmcnt(6)
	v_mfma_f32_32x32x16_bf16 v[30:45], v[82:85], v[186:189], v[30:45]
	ds_read_b64_tr_b16 v[186:187], v167 offset:0x1200
	ds_read_b64_tr_b16 v[188:189], v167 offset:0x1600
	s_waitcnt lgkmcnt(6)
	v_mfma_f32_32x32x16_bf16 v[30:45], v[86:89], v[202:205], v[30:45]
	ds_read_b64_tr_b16 v[202:203], v167 offset:0x1a00
	ds_read_b64_tr_b16 v[204:205], v167 offset:0x1e00
	s_waitcnt lgkmcnt(6)
	v_mfma_f32_32x32x16_bf16 v[14:29], v[8:11], v[160:163], v[14:29]
	v_max_f32_e32 v8, v94, v95
	v_max3_f32 v8, v8, v96, v97
	v_max3_f32 v8, v8, v98, v99
	v_max3_f32 v8, v8, v100, v101
	v_max3_f32 v8, v8, v102, v103
	s_waitcnt lgkmcnt(4)
	v_mfma_f32_32x32x16_bf16 v[14:29], v[78:81], v[182:185], v[14:29]
	v_max3_f32 v8, v8, v104, v105
	v_max3_f32 v8, v8, v106, v107
	v_max3_f32 v8, v8, v108, v109
	v_max3_f32 v8, v8, v62, v63
	v_max3_f32 v8, v8, v64, v65
	v_max3_f32 v8, v8, v66, v67
	v_max3_f32 v8, v8, v68, v69
	s_waitcnt lgkmcnt(2)
	v_mfma_f32_32x32x16_bf16 v[14:29], v[82:85], v[186:189], v[14:29]
	v_max3_f32 v8, v8, v70, v71
	v_max3_f32 v8, v8, v72, v73
	v_max3_f32 v8, v8, v74, v75
	v_max3_f32 v8, v8, v76, v77
	v_mov_b32_e32 v9, v8
	s_nop 1
	v_permlane32_swap_b32_e32 v8, v9
	s_waitcnt lgkmcnt(0)
	v_mfma_f32_32x32x16_bf16 v[14:29], v[86:89], v[202:205], v[14:29]
	v_max_f32_e32 v9, v8, v9
	v_cmp_ge_f32_e32 vcc, s33, v9
	s_cmp_eq_u64 vcc, exec
	s_cselect_b32 s100, 0, 1
	v_mov_b32_e32 v8, 1.0
	s_cbranch_scc1 .LBB0_1167
	v_max_f32_e32 v8, v9, v9
	v_max_f32_e32 v10, 0, v8
	v_exp_f32_e64 v8, -v10
	v_add_f32_e32 v168, v168, v10
	v_xor_b32_e32 v46, 0x80000000, v168
	v_pk_add_f32 v[94:95], v[94:95], v[10:11] op_sel_hi:[1,0] neg_lo:[0,1] neg_hi:[0,1]
	v_pk_add_f32 v[96:97], v[96:97], v[10:11] op_sel_hi:[1,0] neg_lo:[0,1] neg_hi:[0,1]
	v_pk_add_f32 v[98:99], v[98:99], v[10:11] op_sel_hi:[1,0] neg_lo:[0,1] neg_hi:[0,1]
	v_pk_add_f32 v[100:101], v[100:101], v[10:11] op_sel_hi:[1,0] neg_lo:[0,1] neg_hi:[0,1]
	v_pk_add_f32 v[102:103], v[102:103], v[10:11] op_sel_hi:[1,0] neg_lo:[0,1] neg_hi:[0,1]
	v_pk_add_f32 v[104:105], v[104:105], v[10:11] op_sel_hi:[1,0] neg_lo:[0,1] neg_hi:[0,1]
	v_pk_add_f32 v[106:107], v[106:107], v[10:11] op_sel_hi:[1,0] neg_lo:[0,1] neg_hi:[0,1]
	v_pk_add_f32 v[108:109], v[108:109], v[10:11] op_sel_hi:[1,0] neg_lo:[0,1] neg_hi:[0,1]
	v_sub_f32_e32 v77, v77, v10
	v_sub_f32_e32 v76, v76, v10
	v_sub_f32_e32 v75, v75, v10
	v_sub_f32_e32 v74, v74, v10
	v_sub_f32_e32 v73, v73, v10
	v_sub_f32_e32 v72, v72, v10
	v_sub_f32_e32 v71, v71, v10
	v_sub_f32_e32 v70, v70, v10
	v_sub_f32_e32 v69, v69, v10
	v_sub_f32_e32 v68, v68, v10
	v_sub_f32_e32 v67, v67, v10
	v_sub_f32_e32 v66, v66, v10
	v_sub_f32_e32 v65, v65, v10
	v_sub_f32_e32 v64, v64, v10
	v_sub_f32_e32 v63, v63, v10
	v_sub_f32_e32 v62, v62, v10
	v_mov_b32_e32 v47, v46
	v_mov_b32_e32 v48, v46
	v_mov_b32_e32 v49, v46
	v_mov_b32_e32 v50, v46
	v_mov_b32_e32 v51, v46
	v_mov_b32_e32 v52, v46
	v_mov_b32_e32 v53, v46
	v_mov_b32_e32 v54, v46
	v_mov_b32_e32 v55, v46
	v_mov_b32_e32 v56, v46
	v_mov_b32_e32 v57, v46
	v_mov_b32_e32 v58, v46
	v_mov_b32_e32 v59, v46
	v_mov_b32_e32 v60, v46
	v_mov_b32_e32 v61, v46
.LBB0_1167:
	s_barrier
	s_waitcnt vmcnt(0)
	ds_write_b128 v169, v[4:7] offset:8192
	ds_write_b128 v170, v[0:3] offset:32768
	s_and_saveexec_b64 s[16:17], s[42:43]
	ds_write_b128 v173, v[138:141] offset:32768
	s_or_b64 exec, exec, s[16:17]
	s_cmp_eq_u32 s100, 0
	s_cbranch_scc1 .LBB0_1173
	s_and_saveexec_b64 s[16:17], s[40:41]
	ds_write_b32 v165, v8 offset:49280
	s_or_b64 exec, exec, s[16:17]
	s_waitcnt lgkmcnt(0)
	v_add_u32_e32 v9, v153, v150
	ds_read_b128 v[0:3], v9 offset:49376
	ds_read_b128 v[4:7], v9 offset:49344
	ds_read_b128 v[78:81], v9 offset:49312
	ds_read_b128 v[82:85], v9 offset:49280
	s_waitcnt lgkmcnt(3)
	v_pk_mul_f32 v[42:43], v[42:43], v[0:1]
	s_waitcnt lgkmcnt(2)
	v_pk_mul_f32 v[38:39], v[38:39], v[4:5]
	s_waitcnt lgkmcnt(1)
	v_pk_mul_f32 v[34:35], v[34:35], v[78:79]
	v_pk_mul_f32 v[44:45], v[44:45], v[2:3]
	v_pk_mul_f32 v[40:41], v[40:41], v[6:7]
	v_pk_mul_f32 v[36:37], v[36:37], v[80:81]
	s_waitcnt lgkmcnt(0)
	v_pk_mul_f32 v[32:33], v[32:33], v[84:85]
	v_pk_mul_f32 v[30:31], v[30:31], v[82:83]
	v_pk_mul_f32 v[26:27], v[26:27], v[0:1]
	v_pk_mul_f32 v[22:23], v[22:23], v[4:5]
	v_pk_mul_f32 v[18:19], v[18:19], v[78:79]
	v_pk_mul_f32 v[28:29], v[28:29], v[2:3]
	v_pk_mul_f32 v[24:25], v[24:25], v[6:7]
	v_pk_mul_f32 v[20:21], v[20:21], v[80:81]
	v_pk_mul_f32 v[16:17], v[16:17], v[84:85]
	v_pk_mul_f32 v[14:15], v[14:15], v[82:83]
.LBB0_1173:
	v_exp_f32_e32 v203, v94
	v_exp_f32_e32 v205, v95
	v_exp_f32_e32 v189, v96
	v_exp_f32_e32 v204, v97
	v_exp_f32_e32 v187, v98
	v_exp_f32_e32 v202, v99
	v_exp_f32_e32 v186, v100
	v_exp_f32_e32 v188, v101
	v_exp_f32_e32 v183, v102
	v_exp_f32_e32 v185, v103
	v_exp_f32_e32 v163, v104
	v_exp_f32_e32 v184, v105
	v_exp_f32_e32 v161, v106
	v_exp_f32_e32 v182, v107
	v_exp_f32_e32 v160, v108
	v_exp_f32_e32 v162, v109
	v_fma_f32 v0, v179, v166, v13
	v_fma_f32 v166, v0, v181, v90
	v_add_u32_e32 v154, 0x30000, v154
	v_add_u32_e32 v156, 0x20000, v156
	v_add_u32_e32 v158, 0x30000, v158
	s_add_i32 s18, s18, 2
	s_and_b64 vcc, exec, s[0:1]
	s_waitcnt lgkmcnt(0)
	s_barrier
	s_cbranch_vccnz .LBB0_1175
	v_mov_b32_e32 v179, v8
	s_branch .LBB0_1151
; #define SBAR() __builtin_amdgcn_sched_barrier(0)
; #define QKT(P0, P1, KP) do { if constexpr (PRE) qkt<ND0>(P0, P1, KP, qr, r32, hi, negm); else qkt<ND0>(P0, P1, KP, qr, r32, hi); } while (0)
; DEVFI void partialSM2(f32x16& p0, f32x16& p1, float& mhat, f32x16& negm, float& alpha, const float thr2, const bool first) {
;     float pmax = p0[0];
; #pragma unroll
;     for (int r = 1; r < 16; ++r) pmax = fmaxf(pmax, p0[r]);
; #pragma unroll
;     for (int r = 0; r < 16; ++r) pmax = fmaxf(pmax, p1[r]);
;     { auto rr = __builtin_amdgcn_permlane32_swap(__float_as_uint(pmax), __float_as_uint(pmax), false, false);
;       pmax = fmaxf(__uint_as_float(rr[0]), __uint_as_float(rr[1])); }
;     alpha = 1.f;
;     if (first || !__all(pmax <= thr2)) {
;         const float dl = first ? pmax : fmaxf(pmax, 0.f);
;         mhat += dl; alpha = first ? 1.f : __builtin_amdgcn_exp2f(-dl);
; #pragma unroll
;         for (int r = 0; r < 16; ++r) { p0[r] -= dl; p1[r] -= dl; }
; #pragma unroll
;         for (int r = 0; r < 16; ++r) negm[r] = -mhat;
;         asm volatile("" : "+v"(negm));
;     }
; #pragma unroll
;     for (int r = 0; r < 16; ++r) p0[r] = __builtin_amdgcn_exp2f(p0[r]);
; }
; DEVFI void finishSM(f32x16& p0, f32x16& p1, float alpha, float& l_reg, bf16x8& pa0, bf16x8& pa1, bf16x8& pa2, bf16x8& pa3) {
; #pragma unroll
;     for (int r = 0; r < 16; ++r) p1[r] = __builtin_amdgcn_exp2f(p1[r]);
;     float ps = 0;
; #pragma unroll
;     for (int r = 0; r < 16; ++r) ps += p0[r];
; #pragma unroll
;     for (int r = 0; r < 16; ++r) ps += p1[r];
;     { auto rr = __builtin_amdgcn_permlane32_swap(__float_as_uint(ps), __float_as_uint(ps), false, false);
;       ps = __uint_as_float(rr[0]) + __uint_as_float(rr[1]); }
;     l_reg = l_reg * alpha + ps;
;     ...
;     PK4(p0, 0, pa0); PK4(p0, 8, pa1); PK4(p1, 0, pa2); PK4(p1, 8, pa3);
;     ...
; }
; template <int DQK, int DV, bool PRE = false>
; DEVFI void attn_unit(const bf16_t* __restrict__ Qb, int ldq, const bf16_t* __restrict__ Kh, int ldk, const bf16_t* __restrict__ Vh, int ldv,
;                      bf16_t* __restrict__ Ob, int ldo, int seq, float scale, char* lds) {
;     ...
;     SBAR(); QKT(pB0, pB1, K_lds + SHM_K);
;     finishSM(pA0, pA1, alA, l_reg, pa0, pa1, pa2, pa3); SBAR();
;     pv_all<NCB>(o, vb0, pa0, pa1, pa2, pa3); PSM(pB0, pB1, mnB, alB, false);
;     __syncthreads(); RESC(alB);
.LBB0_1175:
	v_mov_b32_e32 v238, v166
	s_nop 1
	v_permlane32_swap_b32_e32 v166, v238
	v_add_f32_e32 v166, v166, v238
	ds_read_b128 v[0:3], v177 offset:32768
	ds_read_b128 v[4:7], v177 offset:40960
	v_exp_f32_e32 v9, v64
	v_exp_f32_e32 v10, v65
	v_exp_f32_e32 v11, v66
	s_waitcnt lgkmcnt(1)
	v_mfma_f32_32x32x16_bf16 v[78:93], v[0:3], v[130:133], v[46:61]
	v_exp_f32_e32 v13, v67
	v_exp_f32_e32 v94, v68
	v_exp_f32_e32 v69, v69
	v_exp_f32_e32 v70, v70
	v_exp_f32_e32 v71, v71
	v_exp_f32_e32 v72, v72
	v_exp_f32_e32 v73, v73
	s_waitcnt lgkmcnt(0)
	v_mfma_f32_32x32x16_bf16 v[46:61], v[4:7], v[130:133], v[46:61]
	ds_read_b128 v[0:3], v178 offset:32768
	ds_read_b128 v[4:7], v178 offset:40960
	v_exp_f32_e32 v74, v74
	v_exp_f32_e32 v75, v75
	v_exp_f32_e32 v76, v76
	v_exp_f32_e32 v77, v77
	s_waitcnt lgkmcnt(1)
	v_mfma_f32_32x32x16_bf16 v[78:93], v[0:3], v[126:129], v[78:93]
	s_waitcnt lgkmcnt(0)
	v_mfma_f32_32x32x16_bf16 v[46:61], v[4:7], v[126:129], v[46:61]
	ds_read_b128 v[0:3], v176 offset:32768
	ds_read_b128 v[4:7], v176 offset:40960
	s_waitcnt lgkmcnt(1)
	v_mfma_f32_32x32x16_bf16 v[78:93], v[0:3], v[122:125], v[78:93]
	s_waitcnt lgkmcnt(0)
	v_mfma_f32_32x32x16_bf16 v[46:61], v[4:7], v[122:125], v[46:61]
	ds_read_b128 v[0:3], v175 offset:32768
	ds_read_b128 v[4:7], v175 offset:40960
	s_waitcnt lgkmcnt(1)
	v_mfma_f32_32x32x16_bf16 v[78:93], v[0:3], v[118:121], v[78:93]
	s_waitcnt lgkmcnt(0)
	v_mfma_f32_32x32x16_bf16 v[46:61], v[4:7], v[118:121], v[46:61]
	ds_read_b128 v[0:3], v174 offset:32768
	ds_read_b128 v[4:7], v174 offset:40960
	s_waitcnt lgkmcnt(1)
	v_mfma_f32_32x32x16_bf16 v[78:93], v[0:3], v[114:117], v[78:93]
	s_waitcnt lgkmcnt(0)
	v_mfma_f32_32x32x16_bf16 v[46:61], v[4:7], v[114:117], v[46:61]
	ds_read_b128 v[0:3], v172 offset:32768
	ds_read_b128 v[4:7], v172 offset:40960
	s_waitcnt lgkmcnt(1)
	v_mfma_f32_32x32x16_bf16 v[78:93], v[0:3], v[110:113], v[78:93]
	v_add_f32_e32 v0, 0, v203
	v_add_f32_e32 v0, v205, v0
	v_add_f32_e32 v0, v189, v0
	v_add_f32_e32 v0, v204, v0
	v_add_f32_e32 v0, v187, v0
	v_add_f32_e32 v0, v202, v0
	v_add_f32_e32 v0, v186, v0
	v_add_f32_e32 v0, v188, v0
	v_add_f32_e32 v0, v183, v0
	v_add_f32_e32 v0, v185, v0
	v_add_f32_e32 v0, v163, v0
	v_add_f32_e32 v0, v184, v0
	s_waitcnt lgkmcnt(0)
	v_mfma_f32_32x32x16_bf16 v[46:61], v[4:7], v[110:113], v[46:61]
	v_exp_f32_e32 v6, v62
	v_add_f32_e32 v0, v161, v0
	v_exp_f32_e32 v7, v63
	v_add_f32_e32 v0, v182, v0
	v_add_f32_e32 v0, v160, v0
	v_add_f32_e32 v0, v162, v0
	v_add_f32_e32 v0, v6, v0
	v_add_f32_e32 v0, v7, v0
	v_add_f32_e32 v0, v9, v0
	v_add_f32_e32 v0, v10, v0
	v_add_f32_e32 v0, v11, v0
	v_add_f32_e32 v0, v13, v0
	v_add_f32_e32 v0, v94, v0
	v_add_f32_e32 v0, v69, v0
	v_add_f32_e32 v0, v70, v0
	v_add_f32_e32 v0, v71, v0
	v_add_f32_e32 v0, v72, v0
	v_add_f32_e32 v0, v73, v0
	v_add_f32_e32 v0, v74, v0
	v_add_f32_e32 v0, v75, v0
	v_add_f32_e32 v0, v76, v0
	v_add_f32_e32 v0, v77, v0
	v_mov_b32_e32 v1, v0
	v_cvt_pk_bf16_f32 v2, v203, v205
	v_cvt_pk_bf16_f32 v3, v189, v204
	v_cvt_pk_bf16_f32 v4, v187, v202
	v_cvt_pk_bf16_f32 v5, v186, v188
	s_nop 1
	v_permlane32_swap_b32_e32 v0, v1
	v_permlane32_swap_b32_e32 v2, v4
	v_permlane32_swap_b32_e32 v3, v5
	v_cvt_pk_bf16_f32 v62, v183, v185
	v_cvt_pk_bf16_f32 v63, v163, v184
	v_cvt_pk_bf16_f32 v64, v161, v182
	v_cvt_pk_bf16_f32 v65, v160, v162
	v_cvt_pk_bf16_f32 v66, v6, v7
	v_cvt_pk_bf16_f32 v67, v9, v10
	v_cvt_pk_bf16_f32 v68, v11, v13
	v_cvt_pk_bf16_f32 v69, v94, v69
	v_cvt_pk_bf16_f32 v70, v70, v71
	v_cvt_pk_bf16_f32 v71, v72, v73
	v_cvt_pk_bf16_f32 v72, v74, v75
	v_cvt_pk_bf16_f32 v73, v76, v77
	s_nop 0
	v_permlane32_swap_b32_e32 v62, v64
	v_permlane32_swap_b32_e32 v63, v65
	v_permlane32_swap_b32_e32 v66, v68
	v_permlane32_swap_b32_e32 v67, v69
	v_permlane32_swap_b32_e32 v70, v72
	v_permlane32_swap_b32_e32 v71, v73
	ds_read_b64_tr_b16 v[74:75], v171 offset:0
	ds_read_b64_tr_b16 v[76:77], v171 offset:0x400
	ds_read_b64_tr_b16 v[94:95], v171 offset:0x800
	ds_read_b64_tr_b16 v[96:97], v171 offset:0xc00
	ds_read_b64_tr_b16 v[98:99], v171 offset:0x1000
	ds_read_b64_tr_b16 v[100:101], v171 offset:0x1400
	ds_read_b64_tr_b16 v[102:103], v171 offset:0x1800
	ds_read_b64_tr_b16 v[104:105], v171 offset:0x1c00
	s_waitcnt lgkmcnt(0)
	s_nop 0
	v_mfma_f32_32x32x16_bf16 v[30:45], v[2:5], v[74:77], v[30:45]
	ds_read_b64_tr_b16 v[74:75], v171 offset:0x200
	ds_read_b64_tr_b16 v[76:77], v171 offset:0x600
	v_mfma_f32_32x32x16_bf16 v[30:45], v[62:65], v[94:97], v[30:45]
	ds_read_b64_tr_b16 v[94:95], v171 offset:0xa00
	ds_read_b64_tr_b16 v[96:97], v171 offset:0xe00
	v_mfma_f32_32x32x16_bf16 v[30:45], v[66:69], v[98:101], v[30:45]
	ds_read_b64_tr_b16 v[98:99], v171 offset:0x1200
	ds_read_b64_tr_b16 v[100:101], v171 offset:0x1600
	v_mfma_f32_32x32x16_bf16 v[30:45], v[70:73], v[102:105], v[30:45]
	ds_read_b64_tr_b16 v[102:103], v171 offset:0x1a00
	ds_read_b64_tr_b16 v[104:105], v171 offset:0x1e00
	s_waitcnt lgkmcnt(0)
	v_mfma_f32_32x32x16_bf16 v[14:29], v[2:5], v[74:77], v[14:29]
	v_max_f32_e32 v2, v79, v79
	v_max_f32_e32 v3, v78, v78
	v_max_f32_e32 v2, v3, v2
	v_max3_f32 v2, v2, v80, v81
	v_max3_f32 v2, v2, v82, v83
	v_max3_f32 v2, v2, v84, v85
	v_max3_f32 v2, v2, v86, v87
	v_mfma_f32_32x32x16_bf16 v[14:29], v[62:65], v[94:97], v[14:29]
	v_max3_f32 v2, v2, v88, v89
	v_max3_f32 v2, v2, v90, v91
	v_max3_f32 v2, v2, v92, v93
	v_max3_f32 v2, v2, v46, v47
	v_max3_f32 v2, v2, v48, v49
	v_max3_f32 v2, v2, v50, v51
	v_max3_f32 v2, v2, v52, v53
	v_mfma_f32_32x32x16_bf16 v[14:29], v[66:69], v[98:101], v[14:29]
	v_max3_f32 v2, v2, v54, v55
	v_max3_f32 v2, v2, v56, v57
	v_max3_f32 v2, v2, v58, v59
	v_max3_f32 v2, v2, v60, v61
	v_mov_b32_e32 v3, v2
	s_nop 1
	v_permlane32_swap_b32_e32 v2, v3
	v_mfma_f32_32x32x16_bf16 v[14:29], v[70:73], v[102:105], v[14:29]
	v_max_f32_e32 v3, v3, v3
	v_max_f32_e32 v2, v2, v2
	v_max_f32_e32 v3, v2, v3
	v_cmp_ge_f32_e32 vcc, s33, v3
	s_cmp_eq_u64 vcc, exec
	v_mov_b32_e32 v2, 1.0
	s_cbranch_scc1 .LBB0_1177
; DEVFI void partialSM2(f32x16& p0, f32x16& p1, float& mhat, f32x16& negm, float& alpha, const float thr2, const bool first) {
;     ...
;     if (first || !__all(pmax <= thr2)) {
;         const float dl = first ? pmax : fmaxf(pmax, 0.f);
;         mhat += dl; alpha = first ? 1.f : __builtin_amdgcn_exp2f(-dl);
; #pragma unroll
;         for (int r = 0; r < 16; ++r) { p0[r] -= dl; p1[r] -= dl; }
; #pragma unroll
;         for (int r = 0; r < 16; ++r) negm[r] = -mhat;
;         asm volatile("" : "+v"(negm));
	v_max_f32_e32 v2, v3, v3
	v_max_f32_e32 v4, 0, v2
	v_exp_f32_e64 v2, -v4
	v_add_f32_e32 v3, v168, v4
	v_xor_b32_e32 v62, 0x80000000, v3
	v_pk_add_f32 v[78:79], v[78:79], v[4:5] op_sel_hi:[1,0] neg_lo:[0,1] neg_hi:[0,1]
	v_pk_add_f32 v[80:81], v[80:81], v[4:5] op_sel_hi:[1,0] neg_lo:[0,1] neg_hi:[0,1]
	v_pk_add_f32 v[82:83], v[82:83], v[4:5] op_sel_hi:[1,0] neg_lo:[0,1] neg_hi:[0,1]
	v_pk_add_f32 v[84:85], v[84:85], v[4:5] op_sel_hi:[1,0] neg_lo:[0,1] neg_hi:[0,1]
	v_pk_add_f32 v[86:87], v[86:87], v[4:5] op_sel_hi:[1,0] neg_lo:[0,1] neg_hi:[0,1]
	v_pk_add_f32 v[88:89], v[88:89], v[4:5] op_sel_hi:[1,0] neg_lo:[0,1] neg_hi:[0,1]
	v_pk_add_f32 v[90:91], v[90:91], v[4:5] op_sel_hi:[1,0] neg_lo:[0,1] neg_hi:[0,1]
	v_pk_add_f32 v[92:93], v[92:93], v[4:5] op_sel_hi:[1,0] neg_lo:[0,1] neg_hi:[0,1]
	v_sub_f32_e32 v61, v61, v4
	v_sub_f32_e32 v60, v60, v4
	v_sub_f32_e32 v59, v59, v4
	v_sub_f32_e32 v58, v58, v4
	v_sub_f32_e32 v57, v57, v4
	v_sub_f32_e32 v56, v56, v4
	v_sub_f32_e32 v55, v55, v4
	v_sub_f32_e32 v54, v54, v4
	v_sub_f32_e32 v53, v53, v4
	v_sub_f32_e32 v52, v52, v4
	v_sub_f32_e32 v51, v51, v4
	v_sub_f32_e32 v50, v50, v4
	v_sub_f32_e32 v49, v49, v4
	v_sub_f32_e32 v48, v48, v4
	v_sub_f32_e32 v47, v47, v4
	v_sub_f32_e32 v46, v46, v4
	v_mov_b32_e32 v63, v62
	v_mov_b32_e32 v64, v62
	v_mov_b32_e32 v65, v62
	v_mov_b32_e32 v66, v62
	v_mov_b32_e32 v67, v62
	v_mov_b32_e32 v68, v62
	v_mov_b32_e32 v69, v62
	v_mov_b32_e32 v70, v62
	v_mov_b32_e32 v71, v62
	v_mov_b32_e32 v72, v62
	v_mov_b32_e32 v73, v62
	v_mov_b32_e32 v74, v62
	v_mov_b32_e32 v75, v62
	v_mov_b32_e32 v76, v62
	v_mov_b32_e32 v77, v62
